# attention queues: the four FoX (batch, head) streams of an XCD interleaved item by item instead of two at a time
# baseline (speedup 1.0000x reference)
.LBB0_835:
	s_or_b64 exec, exec, s[0:1]
	s_waitcnt lgkmcnt(0)
	s_barrier
	ds_read_b32 v0, v202
	s_movk_i32 s0, 0x20b
	s_waitcnt lgkmcnt(0)
	s_barrier
	v_cmp_lt_i32_e32 vcc, s0, v0
	v_readfirstlane_b32 s54, v0
	s_mov_b64 s[0:1], -1
	s_cbranch_vccnz .LBB0_830
	s_cmp_lt_i32 s54, 8
	s_cbranch_scc1 .LBB0_846
	s_mov_b64 s[36:37], -1
	s_cmp_gt_u32 s54, 11
	s_mov_b64 s[38:39], -1
	s_cbranch_scc0 .LBB0_843
	s_mov_b64 s[4:5], -1
	s_cmpk_gt_u32 s54, 0x10b
	s_cbranch_scc0 .LBB0_840
	s_add_i32 s6, s54, 0xfffffef4
	s_and_b32 s30, s6, 2
	s_add_i32 s30, s30, s70
	s_not_b32 s6, s6
	s_and_b32 s31, s54, 1
	s_bfe_u32 s50, s6, 0x60002
	s_and_b32 s6, s30, 6
	s_lshr_b32 s55, s30, 3
	s_or_b32 s6, s6, s31
	s_mov_b64 s[38:39], 0
